# LoRA GEMM static unit mapping rebalanced by epilogue cost (light units to 5-unit WGs)
# baseline (speedup 1.0000x reference)
.LBB0_636:
	s_and_b64 vcc, exec, s[24:25]
	s_cbranch_vccz .LBB0_880
	v_readlane_b32 s12, v254, 30
	s_waitcnt vmcnt(0)
	v_mbcnt_lo_u32_b32 v20, -1, 0
	v_mbcnt_hi_u32_b32 v20, -1, v20
	s_movk_i32 s42, 0x100
	v_lshl_add_u32 v0, s12, 6, v20
	s_movk_i32 s12, 0x800
	s_ashr_i32 s13, s12, 31
	s_lshr_b32 s13, s13, 24
	s_add_i32 s12, s12, s13
	s_ashr_i32 s12, s12, 8
	s_mul_i32 s48, s12, 0x88
	v_readlane_b32 s13, v254, 29
	s_cmp_lt_i32 s13, s48
	v_readfirstlane_b32 s44, v0
	s_cselect_b64 s[24:25], -1, 0
	s_cmp_ge_i32 s13, s48
	s_mul_i32 s34, s12, 17
	s_cbranch_scc1 .LBB0_639
	s_cmp_lt_u32 s13, 64
	s_cbranch_scc0 .Llmap0_big
	s_lshl_b32 s26, s13, 2
	s_branch .Llmap0_light
.Llmap0_big:
	s_sub_i32 s26, s13, 64
	s_lshl_b32 s26, s26, 2
	s_add_i32 s27, s26, 64
	s_cmpk_lt_u32 s26, 0x2f0
	s_cbranch_scc1 .Llmap0_heavy
	s_sub_i32 s26, s26, 0x1f0
.Llmap0_light:
	s_and_b32 s54, s26, 1
	s_or_b32 s54, s54, 6
	s_lshr_b32 s55, s26, 1
	s_branch .Llmap0_done
.Llmap0_heavy:
	s_mul_hi_u32 s55, s27, 0x2aaaaaab
	s_mul_i32 s26, s55, 6
	s_sub_i32 s26, s27, s26
	s_lshl_b32 s26, s26, 2
	s_lshr_b32 s54, 0x524130, s26
	s_and_b32 s54, s54, 7
.Llmap0_done:
.LBB0_639:
	s_andn2_b64 vcc, exec, s[24:25]
	s_cbranch_vccnz .LBB0_880
	v_ashrrev_i32_e32 v3, 31, v0
	v_lshrrev_b32_e32 v3, 26, v3
	v_lshlrev_b32_e32 v2, 4, v0
	v_add_u32_e32 v3, v0, v3
	v_bfe_i32 v0, v0, 27, 1
	v_lshrrev_b32_e32 v0, 22, v0
	v_add_u32_e32 v0, v2, v0
	v_and_b32_e32 v0, 0xfffffc00, v0
	v_sub_u32_e32 v0, v2, v0
	v_lshrrev_b32_e32 v4, 4, v0
	v_bitop3_b32 v0, v4, v0, 32 bitop3:0x6c
	v_ashrrev_i32_e32 v5, 31, v0
	v_ashrrev_i32_e32 v3, 6, v3
	v_lshrrev_b32_e32 v5, 26, v5
	v_lshlrev_b32_e32 v4, 3, v3
	v_add_u32_e32 v5, v0, v5
	v_and_b32_e32 v4, -16, v4
	v_ashrrev_i32_e32 v6, 6, v5
	v_lshlrev_b32_e32 v3, 5, v3
	v_add_u32_e32 v4, v6, v4
	v_and_b32_e32 v14, 32, v3
	v_and_b32_e32 v3, 0xc0, v5
	v_sub_u32_e32 v0, v0, v3
	v_mov_b32_e32 v7, 1
	v_lshlrev_b32_e32 v3, 1, v4
	v_lshrrev_b32_e32 v5, 2, v4
	v_and_b32_e32 v6, 3, v6
	s_mov_b32 s24, 0x7fffffe0
	v_ashrrev_i16_sdwa v0, v7, sext(v0) dst_sel:DWORD dst_unused:UNUSED_PAD src0_sel:DWORD src1_sel:BYTE_0
	v_and_b32_e32 v3, 24, v3
	v_and_b32_e32 v5, 4, v5
	v_and_or_b32 v6, v4, s24, v6
	v_bfe_i32 v15, v0, 0, 16
	v_or3_b32 v3, v6, v5, v3
	v_add_u32_e32 v0, v14, v15
	v_mul_lo_u32 v16, v4, s42
	v_mul_lo_u32 v3, v3, s42
	v_add_u32_e32 v2, 0x2000, v2
	v_add_lshl_u32 v188, v0, v16, 1
	v_add_lshl_u32 v0, v3, v0, 1
	v_ashrrev_i32_e32 v3, 31, v2
	v_lshrrev_b32_e32 v3, 22, v3
	v_add_u32_e32 v3, v2, v3
	v_ashrrev_i32_e32 v3, 10, v3
	v_mul_i32_i24_e32 v4, 0x400, v3
	v_sub_u32_e32 v2, v2, v4
	v_lshrrev_b32_e32 v4, 4, v2
	v_bitop3_b32 v2, v4, v2, 32 bitop3:0x6c
	v_ashrrev_i32_e32 v5, 31, v2
	v_lshrrev_b32_e32 v5, 26, v5
	v_readlane_b32 s13, v254, 40
	v_lshlrev_b32_e32 v4, 3, v3
	v_add_u32_e32 v5, v2, v5
	s_add_u32 s35, s13, 0x2900000
	v_readlane_b32 s13, v254, 39
	v_and_b32_e32 v4, -16, v4
	v_ashrrev_i32_e32 v6, 6, v5
	s_addc_u32 s36, s13, 0
	v_add_u32_e32 v4, v6, v4
	v_and_b32_e32 v6, 3, v6
	s_ashr_i32 s43, s42, 31
	v_and_or_b32 v6, v4, s24, v6
	s_lshl_b64 s[52:53], s[42:43], 9
	s_ashr_i32 s24, s55, 31
	s_mul_i32 s24, s52, s24
	s_mul_hi_u32 s25, s52, s55
	s_ashr_i32 s27, s54, 31
	s_add_i32 s26, s25, s24
	s_lshr_b64 s[24:25], s[42:43], 23
	s_mul_i32 s27, s52, s27
	s_mul_hi_u32 s28, s52, s54
	v_lshlrev_b32_e32 v3, 5, v3
	s_ashr_i32 s45, s44, 6
	s_mul_i32 s25, s24, s55
	s_add_i32 s27, s28, s27
	s_mul_i32 s24, s24, s54
	s_ashr_i32 s13, s44, 8
	v_and_b32_e32 v17, 32, v3
	v_and_b32_e32 v3, 0xc0, v5
	s_lshl_b64 s[50:51], s[42:43], 8
	s_lshl_b32 s37, s45, 10
	s_add_i32 s26, s26, s25
	s_add_i32 s27, s27, s24
	s_mul_i32 s24, s52, s54
	v_sub_u32_e32 v2, v2, v3
	v_lshlrev_b32_e32 v3, 1, v4
	v_lshrrev_b32_e32 v5, 2, v4
	s_add_u32 s46, s35, s24
	v_ashrrev_i16_sdwa v2, v7, sext(v2) dst_sel:DWORD dst_unused:UNUSED_PAD src0_sel:DWORD src1_sel:BYTE_0
	v_and_b32_e32 v3, 24, v3
	v_and_b32_e32 v5, 4, v5
	s_addc_u32 s47, s36, s27
	s_add_i32 s70, s37, 0
	v_bfe_i32 v18, v2, 0, 16
	v_or3_b32 v3, v6, v5, v3
	s_add_i32 m0, s70, 0x10000
	v_add_u32_e32 v2, v17, v18
	v_mul_lo_u32 v3, v3, s42
	global_load_lds_dwordx4 v0, s[46:47]
	s_add_i32 m0, s70, 0x12000
	v_add_lshl_u32 v192, v3, v2, 1
	s_add_u32 s56, s46, s50
	global_load_lds_dwordx4 v192, s[46:47]
	s_addc_u32 s57, s47, s51
	s_add_i32 m0, s70, 0x14000
	s_mul_i32 s25, s52, s55
	global_load_lds_dwordx4 v0, s[56:57]
	s_add_i32 m0, s70, 0x16000
	s_add_u32 s24, s14, s25
	s_addc_u32 s25, s15, s26
	s_add_i32 s71, s70, 0x2000
	v_mul_lo_u32 v19, v4, s42
	global_load_lds_dwordx4 v192, s[56:57]
	s_mov_b32 m0, s70
	s_add_u32 s26, s24, s50
	v_add_lshl_u32 v190, v2, v19, 1
	global_load_lds_dwordx4 v188, s[24:25]
	s_mov_b32 m0, s71
	s_addc_u32 s27, s25, s51
	s_add_i32 s74, s70, 0x4000
	global_load_lds_dwordx4 v190, s[24:25]
	s_mov_b32 m0, s74
	s_add_i32 s75, s70, 0x6000
	global_load_lds_dwordx4 v188, s[26:27]
	s_mov_b32 m0, s75
	v_mov_b32_e32 v193, v1
	global_load_lds_dwordx4 v190, s[26:27]
	s_load_dwordx2 s[30:31], s[0:1], 0x68
	s_load_dwordx2 s[28:29], s[0:1], 0x78
	s_load_dwordx2 s[26:27], s[0:1], 0x98
	s_cmp_eq_u32 s13, 1
	v_lshl_add_u64 v[4:5], s[56:57], 0, v[0:1]
	v_lshl_add_u64 v[2:3], s[56:57], 0, v[192:193]
	s_cselect_b64 s[56:57], -1, 0
	v_mov_b32_e32 v189, v1
	v_mov_b32_e32 v191, v1
	v_writelane_b32 v254, s56, 43
	s_mov_b32 s2, 0x8000
	v_lshl_add_u64 v[10:11], s[46:47], 0, v[0:1]
	v_lshl_add_u64 v[6:7], s[46:47], 0, v[192:193]
	v_lshl_add_u64 v[8:9], s[24:25], 0, v[188:189]
	v_writelane_b32 v254, s57, 44
	s_cmp_lg_u32 s13, 1
	v_lshl_add_u64 v[12:13], s[24:25], 0, v[190:191]
	s_cbranch_scc1 .LBB0_642
	s_barrier

.LBB0_645:
	s_add_i32 s92, s92, 1
	s_mul_i32 s26, s92, s83
	s_mul_hi_u32 s27, s92, s90
	s_add_i32 s27, s27, s26
	s_mul_i32 s26, s92, s90
	v_readlane_b32 s28, v254, 29
	s_add_u32 s26, s26, s28
	s_addc_u32 s27, s27, s84
	v_mov_b64_e32 v[2:3], s[48:49]
	v_cmp_ge_i64_e32 vcc, s[26:27], v[2:3]
	v_cmp_lt_i64_e64 s[44:45], s[26:27], v[2:3]
	s_cbranch_vccnz .LBB0_647
	s_cmp_lt_u32 s28, 64
	s_cbranch_scc0 .Llmap1_big
	s_lshl_b32 s26, s28, 2
	s_add_i32 s26, s26, s92
	s_mov_b32 s27, s28
	s_cmp_eq_u32 s92, 4
	s_cbranch_scc1 .Llmap1_heavy
	s_branch .Llmap1_light
.Llmap1_big:
	s_sub_i32 s26, s28, 64
	s_lshl_b32 s26, s26, 2
	s_add_i32 s26, s26, s92
	s_add_i32 s27, s26, 64
	s_cmpk_lt_u32 s26, 0x2f0
	s_cbranch_scc1 .Llmap1_heavy
	s_sub_i32 s26, s26, 0x1f0
.Llmap1_light:
	s_and_b32 s93, s26, 1
	s_or_b32 s93, s93, 6
	s_lshr_b32 s94, s26, 1
	s_branch .Llmap1_done
.Llmap1_heavy:
	s_mul_hi_u32 s94, s27, 0x2aaaaaab
	s_mul_i32 s26, s94, 6
	s_sub_i32 s26, s27, s26
	s_lshl_b32 s26, s26, 2
	s_lshr_b32 s93, 0x524130, s26
	s_and_b32 s93, s93, 7
.Llmap1_done:
.LBB0_647:
	s_nop 0
	v_cndmask_b32_e64 v2, 0, 1, s[44:45]
	v_cmp_ne_u32_e64 s[42:43], 1, v2
	s_andn2_b64 vcc, exec, s[44:45]
	s_mov_b64 s[64:65], s[24:25]
	s_cbranch_vccnz .LBB0_649
	s_ashr_i32 s26, s94, 31
	s_mul_hi_u32 s27, s52, s94
	s_mul_i32 s26, s52, s26
	s_add_i32 s26, s27, s26
	s_mul_i32 s27, s53, s94
	s_add_i32 s26, s26, s27
	s_mul_i32 s27, s52, s94
	s_add_u32 s64, s14, s27
	s_addc_u32 s65, s15, s26
